# adds: phase-0 adaLN GEMV weight-row loads issued 16 at a time (were one in flight: load, vmcnt(0), use)
# speedup vs baseline: 1.0199x; 1.0140x over previous
.LBB0_614:
	v_lshl_add_u64 v[38:39], v[36:37], 0, s[8:9]
	global_load_dwordx4 v[46:49], v[38:39], off nt
	s_mov_b32 s5, 0
	s_mov_b32 s4, 0x6000
	v_lshl_add_u64 v[92:93], s[4:5], 0, v[38:39]
	global_load_dwordx4 v[92:95], v[92:93], off nt
	s_mov_b32 s4, 0xc000
	v_lshl_add_u64 v[96:97], s[4:5], 0, v[38:39]
	global_load_dwordx4 v[96:99], v[96:97], off nt
	s_mov_b32 s4, 0x12000
	v_lshl_add_u64 v[100:101], s[4:5], 0, v[38:39]
	global_load_dwordx4 v[100:103], v[100:101], off nt
	s_mov_b32 s4, 0x18000
	v_lshl_add_u64 v[104:105], s[4:5], 0, v[38:39]
	global_load_dwordx4 v[104:107], v[104:105], off nt
	s_mov_b32 s4, 0x1e000
	v_lshl_add_u64 v[108:109], s[4:5], 0, v[38:39]
	global_load_dwordx4 v[108:111], v[108:109], off nt
	s_mov_b32 s4, 0x24000
	v_lshl_add_u64 v[112:113], s[4:5], 0, v[38:39]
	global_load_dwordx4 v[112:115], v[112:113], off nt
	s_mov_b32 s4, 0x2a000
	v_lshl_add_u64 v[116:117], s[4:5], 0, v[38:39]
	global_load_dwordx4 v[116:119], v[116:117], off nt
	s_mov_b32 s4, 0x30000
	v_lshl_add_u64 v[120:121], s[4:5], 0, v[38:39]
	global_load_dwordx4 v[120:123], v[120:121], off nt
	s_mov_b32 s4, 0x36000
	v_lshl_add_u64 v[124:125], s[4:5], 0, v[38:39]
	global_load_dwordx4 v[124:127], v[124:125], off nt
	s_mov_b32 s4, 0x3c000
	v_lshl_add_u64 v[128:129], s[4:5], 0, v[38:39]
	global_load_dwordx4 v[128:131], v[128:129], off nt
	s_mov_b32 s4, 0x42000
	v_lshl_add_u64 v[132:133], s[4:5], 0, v[38:39]
	global_load_dwordx4 v[132:135], v[132:133], off nt
	s_mov_b32 s4, 0x48000
	v_lshl_add_u64 v[136:137], s[4:5], 0, v[38:39]
	global_load_dwordx4 v[136:139], v[136:137], off nt
	s_mov_b32 s4, 0x4e000
	v_lshl_add_u64 v[140:141], s[4:5], 0, v[38:39]
	global_load_dwordx4 v[140:143], v[140:141], off nt
	s_mov_b32 s4, 0x54000
	v_lshl_add_u64 v[144:145], s[4:5], 0, v[38:39]
	global_load_dwordx4 v[144:147], v[144:145], off nt
	s_mov_b32 s4, 0x5a000
	v_lshl_add_u64 v[148:149], s[4:5], 0, v[38:39]
	global_load_dwordx4 v[148:151], v[148:149], off nt
	ds_read_b128 v[50:53], v2 offset:4096
	ds_read_b128 v[54:57], v2 offset:8192
	ds_read_b128 v[58:61], v2
	ds_read_b128 v[24:27], v2 offset:16
	ds_read_b128 v[20:23], v2 offset:32
	ds_read_b128 v[16:19], v2 offset:48
	s_mov_b32 s3, 0xc000
	s_add_u32 s8, s8, 0x60000
	s_addc_u32 s9, s9, 0
	s_cmp_eq_u32 s8, 0x180000
	s_waitcnt vmcnt(15) lgkmcnt(3)
	v_pk_fma_f32 v[64:65], v[58:59], v[46:47], v[4:5] op_sel_hi:[0,1,1]
	v_pk_fma_f32 v[62:63], v[58:59], v[48:49], v[6:7] op_sel_hi:[0,1,1]
	s_nop 0
	v_pk_fma_f32 v[8:9], v[46:47], v[50:51], v[8:9] op_sel_hi:[1,0,1]
	v_pk_fma_f32 v[12:13], v[46:47], v[54:55], v[12:13] op_sel_hi:[1,0,1]
	v_pk_fma_f32 v[10:11], v[48:49], v[50:51], v[10:11] op_sel_hi:[1,0,1]
	v_pk_fma_f32 v[14:15], v[48:49], v[54:55], v[14:15] op_sel_hi:[1,0,1]
	s_waitcnt vmcnt(14)
	v_mov_b64_e32 v[4:5], v[92:93]
	v_mov_b64_e32 v[6:7], v[94:95]
	v_pk_fma_f32 v[46:47], v[58:59], v[4:5], v[64:65] op_sel:[1,0,0]
	v_pk_fma_f32 v[8:9], v[4:5], v[50:51], v[8:9] op_sel:[0,1,0]
	v_pk_fma_f32 v[12:13], v[4:5], v[54:55], v[12:13] op_sel:[0,1,0]
	v_pk_fma_f32 v[48:49], v[58:59], v[6:7], v[62:63] op_sel:[1,0,0]
	s_nop 0
	v_pk_fma_f32 v[10:11], v[6:7], v[50:51], v[10:11] op_sel:[0,1,0]
	v_pk_fma_f32 v[14:15], v[6:7], v[54:55], v[14:15] op_sel:[0,1,0]
	s_mov_b32 s3, 0x12000
	v_mov_b32_e32 v50, v61
	s_waitcnt vmcnt(13)
	v_mov_b64_e32 v[4:5], v[96:97]
	v_mov_b64_e32 v[6:7], v[98:99]
	v_pk_fma_f32 v[46:47], v[60:61], v[4:5], v[46:47] op_sel_hi:[0,1,1]
	v_pk_fma_f32 v[8:9], v[4:5], v[52:53], v[8:9] op_sel_hi:[1,0,1]
	v_pk_fma_f32 v[12:13], v[4:5], v[56:57], v[12:13] op_sel_hi:[1,0,1]
	v_pk_fma_f32 v[48:49], v[60:61], v[6:7], v[48:49] op_sel_hi:[0,1,1]
	s_nop 0
	v_pk_fma_f32 v[10:11], v[6:7], v[52:53], v[10:11] op_sel_hi:[1,0,1]
	v_pk_fma_f32 v[14:15], v[6:7], v[56:57], v[14:15] op_sel_hi:[1,0,1]
	s_mov_b32 s3, 0x18000
	s_waitcnt vmcnt(12)
	v_mov_b64_e32 v[4:5], v[100:101]
	v_mov_b64_e32 v[6:7], v[102:103]
	v_pk_fma_f32 v[48:49], v[50:51], v[6:7], v[48:49] op_sel_hi:[0,1,1]
	v_pk_fma_f32 v[46:47], v[50:51], v[4:5], v[46:47] op_sel_hi:[0,1,1]
	v_mov_b32_e32 v50, v53
	v_pk_fma_f32 v[52:53], v[6:7], v[50:51], v[10:11] op_sel_hi:[1,0,1]
	v_pk_fma_f32 v[50:51], v[4:5], v[50:51], v[8:9] op_sel_hi:[1,0,1]
	v_mov_b32_e32 v8, v57
	v_pk_fma_f32 v[56:57], v[4:5], v[8:9], v[12:13] op_sel_hi:[1,0,1]
	v_pk_fma_f32 v[54:55], v[6:7], v[8:9], v[14:15] op_sel_hi:[1,0,1]
	s_nop 0
	ds_read_b128 v[8:11], v2 offset:4112
	ds_read_b128 v[12:15], v2 offset:8208
	s_mov_b32 s3, 0x1e000
	s_waitcnt vmcnt(11) lgkmcnt(4)
	v_mov_b64_e32 v[4:5], v[104:105]
	v_mov_b64_e32 v[6:7], v[106:107]
	v_pk_fma_f32 v[46:47], v[24:25], v[4:5], v[46:47] op_sel_hi:[0,1,1]
	s_waitcnt lgkmcnt(1)
	v_pk_fma_f32 v[50:51], v[4:5], v[8:9], v[50:51] op_sel_hi:[1,0,1]
	s_waitcnt lgkmcnt(0)
	v_pk_fma_f32 v[56:57], v[4:5], v[12:13], v[56:57] op_sel_hi:[1,0,1]
	v_pk_fma_f32 v[48:49], v[24:25], v[6:7], v[48:49] op_sel_hi:[0,1,1]
	s_nop 0
	v_pk_fma_f32 v[52:53], v[6:7], v[8:9], v[52:53] op_sel_hi:[1,0,1]
	v_pk_fma_f32 v[54:55], v[6:7], v[12:13], v[54:55] op_sel_hi:[1,0,1]
	s_mov_b32 s3, 0x24000
	s_waitcnt vmcnt(10)
	v_mov_b64_e32 v[4:5], v[108:109]
	v_mov_b64_e32 v[6:7], v[110:111]
	v_pk_fma_f32 v[48:49], v[24:25], v[6:7], v[48:49] op_sel:[1,0,0]
	v_pk_fma_f32 v[24:25], v[24:25], v[4:5], v[46:47] op_sel:[1,0,0]
	v_pk_fma_f32 v[46:47], v[6:7], v[8:9], v[52:53] op_sel:[0,1,0]
	v_pk_fma_f32 v[8:9], v[4:5], v[8:9], v[50:51] op_sel:[0,1,0]
	v_pk_fma_f32 v[50:51], v[6:7], v[12:13], v[54:55] op_sel:[0,1,0]
	v_pk_fma_f32 v[12:13], v[4:5], v[12:13], v[56:57] op_sel:[0,1,0]
	s_mov_b32 s3, 0x2a000
	s_nop 0
	s_waitcnt vmcnt(9)
	v_mov_b64_e32 v[4:5], v[112:113]
	v_mov_b64_e32 v[6:7], v[114:115]
	v_pk_fma_f32 v[24:25], v[26:27], v[4:5], v[24:25] op_sel_hi:[0,1,1]
	v_pk_fma_f32 v[8:9], v[4:5], v[10:11], v[8:9] op_sel_hi:[1,0,1]
	v_pk_fma_f32 v[12:13], v[4:5], v[14:15], v[12:13] op_sel_hi:[1,0,1]
	v_pk_fma_f32 v[48:49], v[26:27], v[6:7], v[48:49] op_sel_hi:[0,1,1]
	s_nop 0
	v_pk_fma_f32 v[46:47], v[6:7], v[10:11], v[46:47] op_sel_hi:[1,0,1]
	v_pk_fma_f32 v[50:51], v[6:7], v[14:15], v[50:51] op_sel_hi:[1,0,1]
	v_mov_b32_e32 v10, v27
	s_mov_b32 s3, 0x36000
	s_waitcnt vmcnt(8)
	v_mov_b64_e32 v[4:5], v[116:117]
	v_mov_b64_e32 v[6:7], v[118:119]
	v_pk_fma_f32 v[26:27], v[10:11], v[6:7], v[48:49] op_sel_hi:[0,1,1]
	v_pk_fma_f32 v[24:25], v[10:11], v[4:5], v[24:25] op_sel_hi:[0,1,1]
	v_mov_b32_e32 v10, v11
	v_pk_fma_f32 v[48:49], v[4:5], v[10:11], v[8:9] op_sel_hi:[1,0,1]
	v_mov_b32_e32 v8, v15
	v_pk_fma_f32 v[52:53], v[4:5], v[8:9], v[12:13] op_sel_hi:[1,0,1]
	v_pk_fma_f32 v[46:47], v[6:7], v[10:11], v[46:47] op_sel_hi:[1,0,1]
	s_nop 0
	v_pk_fma_f32 v[50:51], v[6:7], v[8:9], v[50:51] op_sel_hi:[1,0,1]
	ds_read_b128 v[8:11], v2 offset:4128
	ds_read_b128 v[12:15], v2 offset:8224
	s_waitcnt vmcnt(7)
	v_mov_b64_e32 v[4:5], v[120:121]
	v_mov_b64_e32 v[6:7], v[122:123]
	v_pk_fma_f32 v[24:25], v[20:21], v[4:5], v[24:25] op_sel_hi:[0,1,1]
	s_waitcnt lgkmcnt(1)
	v_pk_fma_f32 v[48:49], v[4:5], v[8:9], v[48:49] op_sel_hi:[1,0,1]
	s_waitcnt lgkmcnt(0)
	v_pk_fma_f32 v[52:53], v[4:5], v[12:13], v[52:53] op_sel_hi:[1,0,1]
	v_pk_fma_f32 v[26:27], v[20:21], v[6:7], v[26:27] op_sel_hi:[0,1,1]
	s_nop 0
	v_pk_fma_f32 v[46:47], v[6:7], v[8:9], v[46:47] op_sel_hi:[1,0,1]
	v_pk_fma_f32 v[50:51], v[6:7], v[12:13], v[50:51] op_sel_hi:[1,0,1]
	s_mov_b32 s3, 0x3c000
	s_waitcnt vmcnt(6)
	v_mov_b64_e32 v[4:5], v[124:125]
	v_mov_b64_e32 v[6:7], v[126:127]
	v_pk_fma_f32 v[26:27], v[20:21], v[6:7], v[26:27] op_sel:[1,0,0]
	v_pk_fma_f32 v[20:21], v[20:21], v[4:5], v[24:25] op_sel:[1,0,0]
	v_pk_fma_f32 v[24:25], v[6:7], v[8:9], v[46:47] op_sel:[0,1,0]
	v_pk_fma_f32 v[8:9], v[4:5], v[8:9], v[48:49] op_sel:[0,1,0]
	v_pk_fma_f32 v[46:47], v[6:7], v[12:13], v[50:51] op_sel:[0,1,0]
	v_pk_fma_f32 v[12:13], v[4:5], v[12:13], v[52:53] op_sel:[0,1,0]
	s_mov_b32 s3, 0x42000
	s_nop 0
	s_waitcnt vmcnt(5)
	v_mov_b64_e32 v[4:5], v[128:129]
	v_mov_b64_e32 v[6:7], v[130:131]
	v_pk_fma_f32 v[20:21], v[22:23], v[4:5], v[20:21] op_sel_hi:[0,1,1]
	v_pk_fma_f32 v[8:9], v[4:5], v[10:11], v[8:9] op_sel_hi:[1,0,1]
	v_pk_fma_f32 v[12:13], v[4:5], v[14:15], v[12:13] op_sel_hi:[1,0,1]
	v_pk_fma_f32 v[26:27], v[22:23], v[6:7], v[26:27] op_sel_hi:[0,1,1]
	s_nop 0
	v_pk_fma_f32 v[24:25], v[6:7], v[10:11], v[24:25] op_sel_hi:[1,0,1]
	v_pk_fma_f32 v[46:47], v[6:7], v[14:15], v[46:47] op_sel_hi:[1,0,1]
	v_mov_b32_e32 v10, v23
	s_mov_b32 s3, 0x48000
	s_waitcnt vmcnt(4)
	v_mov_b64_e32 v[4:5], v[132:133]
	v_mov_b64_e32 v[6:7], v[134:135]
	v_pk_fma_f32 v[22:23], v[10:11], v[6:7], v[26:27] op_sel_hi:[0,1,1]
	v_pk_fma_f32 v[20:21], v[10:11], v[4:5], v[20:21] op_sel_hi:[0,1,1]
	v_mov_b32_e32 v10, v11
	v_pk_fma_f32 v[26:27], v[4:5], v[10:11], v[8:9] op_sel_hi:[1,0,1]
	v_mov_b32_e32 v8, v15
	v_pk_fma_f32 v[48:49], v[4:5], v[8:9], v[12:13] op_sel_hi:[1,0,1]
	v_pk_fma_f32 v[24:25], v[6:7], v[10:11], v[24:25] op_sel_hi:[1,0,1]
	s_nop 0
	v_pk_fma_f32 v[46:47], v[6:7], v[8:9], v[46:47] op_sel_hi:[1,0,1]
	ds_read_b128 v[8:11], v2 offset:4144
	ds_read_b128 v[12:15], v2 offset:8240
	s_mov_b32 s3, 0x4e000
	v_add_u32_e32 v2, 64, v2
	s_waitcnt vmcnt(3)
	v_mov_b64_e32 v[4:5], v[136:137]
	v_mov_b64_e32 v[6:7], v[138:139]
	v_pk_fma_f32 v[20:21], v[16:17], v[4:5], v[20:21] op_sel_hi:[0,1,1]
	s_waitcnt lgkmcnt(1)
	v_pk_fma_f32 v[26:27], v[4:5], v[8:9], v[26:27] op_sel_hi:[1,0,1]
	s_waitcnt lgkmcnt(0)
	v_pk_fma_f32 v[48:49], v[4:5], v[12:13], v[48:49] op_sel_hi:[1,0,1]
	v_pk_fma_f32 v[22:23], v[16:17], v[6:7], v[22:23] op_sel_hi:[0,1,1]
	s_nop 0
	v_pk_fma_f32 v[24:25], v[6:7], v[8:9], v[24:25] op_sel_hi:[1,0,1]
	v_pk_fma_f32 v[46:47], v[6:7], v[12:13], v[46:47] op_sel_hi:[1,0,1]
	s_mov_b32 s3, 0x54000
	s_waitcnt vmcnt(2)
	v_mov_b64_e32 v[4:5], v[140:141]
	v_mov_b64_e32 v[6:7], v[142:143]
	v_pk_fma_f32 v[22:23], v[16:17], v[6:7], v[22:23] op_sel:[1,0,0]
	v_pk_fma_f32 v[16:17], v[16:17], v[4:5], v[20:21] op_sel:[1,0,0]
	v_pk_fma_f32 v[20:21], v[6:7], v[8:9], v[24:25] op_sel:[0,1,0]
	v_pk_fma_f32 v[8:9], v[4:5], v[8:9], v[26:27] op_sel:[0,1,0]
	v_pk_fma_f32 v[24:25], v[6:7], v[12:13], v[46:47] op_sel:[0,1,0]
	v_pk_fma_f32 v[12:13], v[4:5], v[12:13], v[48:49] op_sel:[0,1,0]
	s_mov_b32 s3, 0x5a000
	s_nop 0
	s_waitcnt vmcnt(1)
	v_mov_b64_e32 v[4:5], v[144:145]
	v_mov_b64_e32 v[6:7], v[146:147]
	v_pk_fma_f32 v[16:17], v[18:19], v[4:5], v[16:17] op_sel_hi:[0,1,1]
	v_pk_fma_f32 v[8:9], v[4:5], v[10:11], v[8:9] op_sel_hi:[1,0,1]
	v_pk_fma_f32 v[12:13], v[4:5], v[14:15], v[12:13] op_sel_hi:[1,0,1]
	v_pk_fma_f32 v[26:27], v[18:19], v[6:7], v[22:23] op_sel_hi:[0,1,1]
	s_nop 0
	v_pk_fma_f32 v[46:47], v[6:7], v[10:11], v[20:21] op_sel_hi:[1,0,1]
	v_mov_b32_e32 v4, v19
	v_pk_fma_f32 v[24:25], v[6:7], v[14:15], v[24:25] op_sel_hi:[1,0,1]
	v_mov_b32_e32 v14, v11
	s_waitcnt vmcnt(0)
	v_mov_b64_e32 v[20:21], v[148:149]
	v_mov_b64_e32 v[22:23], v[150:151]
	v_pk_fma_f32 v[6:7], v[4:5], v[22:23], v[26:27] op_sel_hi:[0,1,1]
	v_pk_fma_f32 v[4:5], v[4:5], v[20:21], v[16:17] op_sel_hi:[0,1,1]
	v_mov_b32_e32 v16, v15
	v_pk_fma_f32 v[10:11], v[22:23], v[14:15], v[46:47] op_sel_hi:[1,0,1]
	v_pk_fma_f32 v[8:9], v[20:21], v[14:15], v[8:9] op_sel_hi:[1,0,1]
	v_pk_fma_f32 v[14:15], v[22:23], v[16:17], v[24:25] op_sel_hi:[1,0,1]
	v_pk_fma_f32 v[12:13], v[20:21], v[16:17], v[12:13] op_sel_hi:[1,0,1]
	s_cbranch_scc0 .LBB0_614
	ds_write_b128 v43, v[4:7] offset:12288
	ds_write_b128 v43, v[8:11] offset:12544
	ds_write_b128 v43, v[12:15] offset:12800
	s_waitcnt lgkmcnt(0)
	s_barrier
	s_and_saveexec_b64 s[4:5], s[0:1]
	s_cbranch_execz .LBB0_605
	ds_read2st64_b32 v[4:5], v45 offset0:48 offset1:51
	s_mul_hi_i32 s3, s2, 0x6000
	v_readlane_b32 s16, v251, 7
	v_readlane_b32 s18, v251, 9
	v_readlane_b32 s19, v251, 10
	s_waitcnt lgkmcnt(0)
	v_add_f32_e32 v2, 0, v4
	v_add_f32_e32 v2, v2, v5
	ds_read2st64_b32 v[4:5], v45 offset0:54 offset1:57
	v_mov_b64_e32 v[8:9], s[18:19]
	v_readlane_b32 s17, v251, 8
	s_waitcnt lgkmcnt(0)
	v_add_f32_e32 v2, v2, v4
	v_add_f32_e32 v2, v2, v5
	ds_read2st64_b32 v[4:5], v45 offset0:60 offset1:63
	s_waitcnt lgkmcnt(0)
	v_add_f32_e32 v2, v2, v4
	v_add_f32_e32 v2, v2, v5
	ds_read2st64_b32 v[4:5], v45 offset0:66 offset1:69
	s_waitcnt lgkmcnt(0)
	v_add_f32_e32 v2, v2, v4
	v_add_f32_e32 v2, v2, v5
	ds_read2st64_b32 v[4:5], v45 offset0:72 offset1:75
	s_waitcnt lgkmcnt(0)
	v_add_f32_e32 v2, v2, v4
	v_add_f32_e32 v2, v2, v5
	ds_read2st64_b32 v[4:5], v45 offset0:78 offset1:81
	s_waitcnt lgkmcnt(0)
	v_add_f32_e32 v2, v2, v4
	v_add_f32_e32 v2, v2, v5
	ds_read2st64_b32 v[4:5], v45 offset0:84 offset1:87
	s_waitcnt lgkmcnt(0)
	v_add_f32_e32 v2, v2, v4
	v_add_f32_e32 v2, v2, v5
	ds_read2st64_b32 v[4:5], v45 offset0:90 offset1:93
	s_waitcnt lgkmcnt(0)
	v_add_f32_e32 v2, v2, v4
	v_or_b32_e32 v4, s6, v44
	s_mul_i32 s6, s2, 0x6000
	v_add_f32_e32 v2, v2, v5
	v_ashrrev_i32_e32 v5, 31, v4
	s_add_u32 s6, s54, s6
	s_addc_u32 s7, s55, s3
	v_lshlrev_b64 v[4:5], 2, v[4:5]
	v_lshl_add_u64 v[6:7], s[6:7], 0, v[4:5]
	global_load_dword v6, v[6:7], off
	s_waitcnt vmcnt(0)
	v_add_f32_e32 v2, v2, v6
	v_mad_i64_i32 v[6:7], s[2:3], s2, 3, v[32:33]
	v_mad_u64_u32 v[8:9], s[2:3], v6, s80, v[8:9]
	v_mad_i32_i24 v9, v7, s80, v9
	v_lshl_add_u64 v[4:5], v[8:9], 0, v[4:5]
	global_store_dword v[4:5], v2, off
	s_branch .LBB0_605
